# speedup vs baseline: 1.0101x; 1.0005x over previous
; __device__ __forceinline__ unsigned xb_add(unsigned* p, unsigned v) { return __hip_atomic_fetch_add(p, v, __ATOMIC_RELAXED, __HIP_MEMORY_SCOPE_AGENT); }
; __device__ __forceinline__ void xcd_barrier(const XcdBarrier& b, unsigned epoch) {
;     ...
;         const unsigned old = xb_add(&bar[XB_XSUB(bx)], 1u);
;         const unsigned gen = epoch;
;         if (old + 1u == (gen + 1u) * bnloc) {
;             __builtin_amdgcn_fence(__ATOMIC_RELEASE, "agent");
;             asm volatile("s_waitcnt vmcnt(0)" ::: "memory");
;             const unsigned og = xb_add(&bar[XB_TOP], 1u);
.LBB0_147:
	s_andn2_saveexec_b64 s[4:5], s[4:5]
	s_cbranch_execz .LBB0_163
	v_mov_b32_e32 v0, s2
	v_add_co_u32_e32 v0, vcc, 0x3000, v0
	v_mov_b32_e32 v1, s3
	s_nop 0
	s_waitcnt vmcnt(0)
	v_addc_co_u32_e32 v1, vcc, 0, v1, vcc
	flat_atomic_add v0, v[0:1], v210 offset:1024 sc0
	s_add_u32 s4, s2, 0x3500
	s_mul_i32 s26, s26, s27
	s_addc_u32 s5, s3, 0
	s_mov_b64 s[8:9], -1
	s_waitcnt vmcnt(0) lgkmcnt(0)
	v_add_u32_e32 v0, 1, v0
	v_cmp_ne_u32_e32 vcc, s26, v0
	v_mov_b64_e32 v[0:1], s[4:5]
	s_and_saveexec_b64 s[6:7], vcc
	s_cbranch_execz .LBB0_160
	v_mov_b64_e32 v[0:1], s[4:5]
	flat_load_dword v0, v[0:1] sc1
	s_mov_b64 s[12:13], 0
	s_waitcnt vmcnt(0) lgkmcnt(0)
	v_cmp_eq_u32_e32 vcc, s25, v0
	s_and_saveexec_b64 s[10:11], vcc
	s_cbranch_execz .LBB0_159
	s_add_u32 s8, s2, 0x200
	s_addc_u32 s9, s3, 0
	s_mov_b32 s26, 1
	s_branch .LBB0_152
